# logf dot-product loop rewritten: all 16 row loads in flight, 8-deep pipelined LDS weight reads (bitwise same math)
# speedup vs baseline: 1.0008x; 1.0008x over previous
; __device__ __forceinline__ float bflo(unsigned w) { return __uint_as_float(w << 16); }
; __device__ __forceinline__ float bfhi(unsigned w) { return __uint_as_float(w & 0xffff0000u); }
; __device__ __forceinline__ void logf_phase(const Args& a, int l, const u64* ssv, LAS unsigned char* lds, int gw, int NGW, int wave, int lane) {
;     ...
;         const bf16_t* hp0 = hbp + (size_t)r0 * DM; const bf16_t* hp1 = hbp + (size_t)r1 * DM;
;         f32x4 h0[8], h1[8];
; #pragma unroll
;         for (int i = 0; i < 8; ++i) { const u32x2 w0 = *(const u32x2*)(hp0 + 4 * lane + 256 * i), w1 = *(const u32x2*)(hp1 + 4 * lane + 256 * i);
;             h0[i] = (f32x4){bflo(w0.x), bfhi(w0.x), bflo(w0.y), bfhi(w0.y)}; h1[i] = (f32x4){bflo(w1.x), bfhi(w1.x), bflo(w1.y), bfhi(w1.y)}; }
;         float sa[8], sb[8];
; #pragma unroll
;         for (int j = 0; j < 8; ++j) { float s0 = 0.f, s1 = 0.f;
; #pragma unroll
;             for (int i = 0; i < 8; ++i) { const f32x4 w = wl[j * (DM / 4) + lane + 64 * i];
;                 s0 += (h0[i][0] * w[0] + h0[i][1] * w[1]) + (h0[i][2] * w[2] + h0[i][3] * w[3]);
;                 s1 += (h1[i][0] * w[0] + h1[i][1] * w[1]) + (h1[i][2] * w[2] + h1[i][3] * w[3]); }
;             sa[j] = s0; sb[j] = s1;
;             __builtin_amdgcn_sched_barrier(0); }
.LBB0_337:
	s_waitcnt lgkmcnt(0)
	ds_read_b128 v[140:143], v3
	ds_read_b128 v[144:147], v3 offset:8192
	ds_read_b128 v[148:151], v3 offset:16384
	ds_read_b128 v[152:155], v3 offset:24576
	ds_read_b128 v[156:159], v3 offset:32768
	ds_read_b128 v[160:163], v3 offset:40960
	ds_read_b128 v[164:167], v3 offset:49152
	ds_read_b128 v[168:171], v3 offset:57344
	v_add_co_u32_e32 v10, vcc, 0x1000, v8
	global_load_dwordx2 v[100:101], v[8:9], off
	s_nop 0
	v_addc_co_u32_e32 v11, vcc, 0, v9, vcc
	global_load_dwordx2 v[116:117], v[10:11], off
	global_load_dwordx2 v[102:103], v[8:9], off offset:512
	global_load_dwordx2 v[118:119], v[10:11], off offset:512
	global_load_dwordx2 v[104:105], v[8:9], off offset:1024
	global_load_dwordx2 v[120:121], v[10:11], off offset:1024
	global_load_dwordx2 v[106:107], v[8:9], off offset:1536
	global_load_dwordx2 v[122:123], v[10:11], off offset:1536
	global_load_dwordx2 v[108:109], v[8:9], off offset:2048
	global_load_dwordx2 v[124:125], v[10:11], off offset:2048
	global_load_dwordx2 v[110:111], v[8:9], off offset:2560
	global_load_dwordx2 v[126:127], v[10:11], off offset:2560
	global_load_dwordx2 v[112:113], v[8:9], off offset:3072
	global_load_dwordx2 v[128:129], v[10:11], off offset:3072
	global_load_dwordx2 v[114:115], v[8:9], off offset:3584
	global_load_dwordx2 v[130:131], v[10:11], off offset:3584
	v_mov_b32_e32 v80, 0
	v_mov_b32_e32 v82, 0
	v_mov_b32_e32 v84, 0
	v_mov_b32_e32 v86, 0
	v_mov_b32_e32 v88, 0
	v_mov_b32_e32 v90, 0
	v_mov_b32_e32 v92, 0
	v_mov_b32_e32 v19, 0
	v_mov_b32_e32 v81, 0
	v_mov_b32_e32 v83, 0
	v_mov_b32_e32 v85, 0
	v_mov_b32_e32 v87, 0
	v_mov_b32_e32 v89, 0
	v_mov_b32_e32 v91, 0
	v_mov_b32_e32 v93, 0
	v_mov_b32_e32 v0, 0
	s_waitcnt vmcnt(14)
	v_lshlrev_b32_e32 v132, 16, v100
	v_and_b32_e32 v133, 0xffff0000, v100
	v_lshlrev_b32_e32 v134, 16, v101
	v_and_b32_e32 v135, 0xffff0000, v101
	v_lshlrev_b32_e32 v136, 16, v116
	v_and_b32_e32 v137, 0xffff0000, v116
	v_lshlrev_b32_e32 v138, 16, v117
	v_and_b32_e32 v139, 0xffff0000, v117
	s_waitcnt lgkmcnt(7)
	v_mul_f32_e32 v172, v141, v133
	v_mul_f32_e32 v174, v141, v137
	v_fmac_f32_e32 v172, v140, v132
	v_fmac_f32_e32 v174, v140, v136
	v_mul_f32_e32 v173, v143, v135
	v_mul_f32_e32 v175, v143, v139
	v_fmac_f32_e32 v173, v142, v134
	v_fmac_f32_e32 v175, v142, v138
	ds_read_b128 v[140:143], v3 offset:1024
	v_add_f32_e32 v172, v172, v173
	v_add_f32_e32 v174, v174, v175
	v_add_f32_e32 v80, v80, v172
	v_add_f32_e32 v81, v81, v174
	s_waitcnt lgkmcnt(7)
	v_mul_f32_e32 v172, v145, v133
	v_mul_f32_e32 v174, v145, v137
	v_fmac_f32_e32 v172, v144, v132
	v_fmac_f32_e32 v174, v144, v136
	v_mul_f32_e32 v173, v147, v135
	v_mul_f32_e32 v175, v147, v139
	v_fmac_f32_e32 v173, v146, v134
	v_fmac_f32_e32 v175, v146, v138
	ds_read_b128 v[144:147], v3 offset:9216
	v_add_f32_e32 v172, v172, v173
	v_add_f32_e32 v174, v174, v175
	v_add_f32_e32 v82, v82, v172
	v_add_f32_e32 v83, v83, v174
	s_waitcnt lgkmcnt(7)
	v_mul_f32_e32 v172, v149, v133
	v_mul_f32_e32 v174, v149, v137
	v_fmac_f32_e32 v172, v148, v132
	v_fmac_f32_e32 v174, v148, v136
	v_mul_f32_e32 v173, v151, v135
	v_mul_f32_e32 v175, v151, v139
	v_fmac_f32_e32 v173, v150, v134
	v_fmac_f32_e32 v175, v150, v138
	ds_read_b128 v[148:151], v3 offset:17408
	v_add_f32_e32 v172, v172, v173
	v_add_f32_e32 v174, v174, v175
	v_add_f32_e32 v84, v84, v172
	v_add_f32_e32 v85, v85, v174
	s_waitcnt lgkmcnt(7)
	v_mul_f32_e32 v172, v153, v133
	v_mul_f32_e32 v174, v153, v137
	v_fmac_f32_e32 v172, v152, v132
	v_fmac_f32_e32 v174, v152, v136
	v_mul_f32_e32 v173, v155, v135
	v_mul_f32_e32 v175, v155, v139
	v_fmac_f32_e32 v173, v154, v134
	v_fmac_f32_e32 v175, v154, v138
	ds_read_b128 v[152:155], v3 offset:25600
	v_add_f32_e32 v172, v172, v173
	v_add_f32_e32 v174, v174, v175
	v_add_f32_e32 v86, v86, v172
	v_add_f32_e32 v87, v87, v174
	s_waitcnt lgkmcnt(7)
	v_mul_f32_e32 v172, v157, v133
	v_mul_f32_e32 v174, v157, v137
	v_fmac_f32_e32 v172, v156, v132
	v_fmac_f32_e32 v174, v156, v136
	v_mul_f32_e32 v173, v159, v135
	v_mul_f32_e32 v175, v159, v139
	v_fmac_f32_e32 v173, v158, v134
	v_fmac_f32_e32 v175, v158, v138
	ds_read_b128 v[156:159], v3 offset:33792
	v_add_f32_e32 v172, v172, v173
	v_add_f32_e32 v174, v174, v175
	v_add_f32_e32 v88, v88, v172
	v_add_f32_e32 v89, v89, v174
	s_waitcnt lgkmcnt(7)
	v_mul_f32_e32 v172, v161, v133
	v_mul_f32_e32 v174, v161, v137
	v_fmac_f32_e32 v172, v160, v132
	v_fmac_f32_e32 v174, v160, v136
	v_mul_f32_e32 v173, v163, v135
	v_mul_f32_e32 v175, v163, v139
	v_fmac_f32_e32 v173, v162, v134
	v_fmac_f32_e32 v175, v162, v138
	ds_read_b128 v[160:163], v3 offset:41984
	v_add_f32_e32 v172, v172, v173
	v_add_f32_e32 v174, v174, v175
	v_add_f32_e32 v90, v90, v172
	v_add_f32_e32 v91, v91, v174
	s_waitcnt lgkmcnt(7)
	v_mul_f32_e32 v172, v165, v133
	v_mul_f32_e32 v174, v165, v137
	v_fmac_f32_e32 v172, v164, v132
	v_fmac_f32_e32 v174, v164, v136
	v_mul_f32_e32 v173, v167, v135
	v_mul_f32_e32 v175, v167, v139
	v_fmac_f32_e32 v173, v166, v134
	v_fmac_f32_e32 v175, v166, v138
	ds_read_b128 v[164:167], v3 offset:50176
	v_add_f32_e32 v172, v172, v173
	v_add_f32_e32 v174, v174, v175
	v_add_f32_e32 v92, v92, v172
	v_add_f32_e32 v93, v93, v174
	s_waitcnt lgkmcnt(7)
	v_mul_f32_e32 v172, v169, v133
	v_mul_f32_e32 v174, v169, v137
	v_fmac_f32_e32 v172, v168, v132
	v_fmac_f32_e32 v174, v168, v136
	v_mul_f32_e32 v173, v171, v135
	v_mul_f32_e32 v175, v171, v139
	v_fmac_f32_e32 v173, v170, v134
	v_fmac_f32_e32 v175, v170, v138
	ds_read_b128 v[168:171], v3 offset:58368
	v_add_f32_e32 v172, v172, v173
	v_add_f32_e32 v174, v174, v175
	v_add_f32_e32 v19, v19, v172
	v_add_f32_e32 v0, v0, v174
	s_waitcnt vmcnt(12)
; __device__ __forceinline__ void logf_phase(const Args& a, int l, const u64* ssv, LAS unsigned char* lds, int gw, int NGW, int wave, int lane) {
;     ...
;         for (int j = 0; j < 8; ++j) { float s0 = 0.f, s1 = 0.f;
; #pragma unroll
;             for (int i = 0; i < 8; ++i) { const f32x4 w = wl[j * (DM / 4) + lane + 64 * i];
;                 s0 += (h0[i][0] * w[0] + h0[i][1] * w[1]) + (h0[i][2] * w[2] + h0[i][3] * w[3]);
;                 s1 += (h1[i][0] * w[0] + h1[i][1] * w[1]) + (h1[i][2] * w[2] + h1[i][3] * w[3]); }
;             sa[j] = s0; sb[j] = s1;
;             __builtin_amdgcn_sched_barrier(0); }
	v_lshlrev_b32_e32 v132, 16, v102
	v_and_b32_e32 v133, 0xffff0000, v102
	v_lshlrev_b32_e32 v134, 16, v103
	v_and_b32_e32 v135, 0xffff0000, v103
	v_lshlrev_b32_e32 v136, 16, v118
	v_and_b32_e32 v137, 0xffff0000, v118
	v_lshlrev_b32_e32 v138, 16, v119
	v_and_b32_e32 v139, 0xffff0000, v119
	s_waitcnt lgkmcnt(7)
	v_mul_f32_e32 v172, v141, v133
	v_mul_f32_e32 v174, v141, v137
	v_fmac_f32_e32 v172, v140, v132
	v_fmac_f32_e32 v174, v140, v136
	v_mul_f32_e32 v173, v143, v135
	v_mul_f32_e32 v175, v143, v139
	v_fmac_f32_e32 v173, v142, v134
	v_fmac_f32_e32 v175, v142, v138
	ds_read_b128 v[140:143], v3 offset:2048
	v_add_f32_e32 v172, v172, v173
	v_add_f32_e32 v174, v174, v175
	v_add_f32_e32 v80, v80, v172
	v_add_f32_e32 v81, v81, v174
	s_waitcnt lgkmcnt(7)
	v_mul_f32_e32 v172, v145, v133
	v_mul_f32_e32 v174, v145, v137
	v_fmac_f32_e32 v172, v144, v132
	v_fmac_f32_e32 v174, v144, v136
	v_mul_f32_e32 v173, v147, v135
	v_mul_f32_e32 v175, v147, v139
	v_fmac_f32_e32 v173, v146, v134
	v_fmac_f32_e32 v175, v146, v138
	ds_read_b128 v[144:147], v3 offset:10240
	v_add_f32_e32 v172, v172, v173
	v_add_f32_e32 v174, v174, v175
	v_add_f32_e32 v82, v82, v172
	v_add_f32_e32 v83, v83, v174
	s_waitcnt lgkmcnt(7)
	v_mul_f32_e32 v172, v149, v133
	v_mul_f32_e32 v174, v149, v137
	v_fmac_f32_e32 v172, v148, v132
	v_fmac_f32_e32 v174, v148, v136
	v_mul_f32_e32 v173, v151, v135
	v_mul_f32_e32 v175, v151, v139
	v_fmac_f32_e32 v173, v150, v134
	v_fmac_f32_e32 v175, v150, v138
	ds_read_b128 v[148:151], v3 offset:18432
	v_add_f32_e32 v172, v172, v173
	v_add_f32_e32 v174, v174, v175
	v_add_f32_e32 v84, v84, v172
	v_add_f32_e32 v85, v85, v174
	s_waitcnt lgkmcnt(7)
	v_mul_f32_e32 v172, v153, v133
	v_mul_f32_e32 v174, v153, v137
	v_fmac_f32_e32 v172, v152, v132
	v_fmac_f32_e32 v174, v152, v136
	v_mul_f32_e32 v173, v155, v135
	v_mul_f32_e32 v175, v155, v139
	v_fmac_f32_e32 v173, v154, v134
	v_fmac_f32_e32 v175, v154, v138
	ds_read_b128 v[152:155], v3 offset:26624
	v_add_f32_e32 v172, v172, v173
	v_add_f32_e32 v174, v174, v175
	v_add_f32_e32 v86, v86, v172
	v_add_f32_e32 v87, v87, v174
	s_waitcnt lgkmcnt(7)
	v_mul_f32_e32 v172, v157, v133
	v_mul_f32_e32 v174, v157, v137
	v_fmac_f32_e32 v172, v156, v132
	v_fmac_f32_e32 v174, v156, v136
	v_mul_f32_e32 v173, v159, v135
	v_mul_f32_e32 v175, v159, v139
	v_fmac_f32_e32 v173, v158, v134
	v_fmac_f32_e32 v175, v158, v138
	ds_read_b128 v[156:159], v3 offset:34816
	v_add_f32_e32 v172, v172, v173
	v_add_f32_e32 v174, v174, v175
	v_add_f32_e32 v88, v88, v172
	v_add_f32_e32 v89, v89, v174
	s_waitcnt lgkmcnt(7)
	v_mul_f32_e32 v172, v161, v133
	v_mul_f32_e32 v174, v161, v137
	v_fmac_f32_e32 v172, v160, v132
	v_fmac_f32_e32 v174, v160, v136
	v_mul_f32_e32 v173, v163, v135
	v_mul_f32_e32 v175, v163, v139
	v_fmac_f32_e32 v173, v162, v134
	v_fmac_f32_e32 v175, v162, v138
	ds_read_b128 v[160:163], v3 offset:43008
	v_add_f32_e32 v172, v172, v173
	v_add_f32_e32 v174, v174, v175
	v_add_f32_e32 v90, v90, v172
	v_add_f32_e32 v91, v91, v174
	s_waitcnt lgkmcnt(7)
	v_mul_f32_e32 v172, v165, v133
	v_mul_f32_e32 v174, v165, v137
	v_fmac_f32_e32 v172, v164, v132
	v_fmac_f32_e32 v174, v164, v136
	v_mul_f32_e32 v173, v167, v135
	v_mul_f32_e32 v175, v167, v139
	v_fmac_f32_e32 v173, v166, v134
	v_fmac_f32_e32 v175, v166, v138
	ds_read_b128 v[164:167], v3 offset:51200
	v_add_f32_e32 v172, v172, v173
	v_add_f32_e32 v174, v174, v175
	v_add_f32_e32 v92, v92, v172
	v_add_f32_e32 v93, v93, v174
	s_waitcnt lgkmcnt(7)
	v_mul_f32_e32 v172, v169, v133
	v_mul_f32_e32 v174, v169, v137
	v_fmac_f32_e32 v172, v168, v132
	v_fmac_f32_e32 v174, v168, v136
	v_mul_f32_e32 v173, v171, v135
	v_mul_f32_e32 v175, v171, v139
	v_fmac_f32_e32 v173, v170, v134
	v_fmac_f32_e32 v175, v170, v138
	ds_read_b128 v[168:171], v3 offset:59392
	v_add_f32_e32 v172, v172, v173
	v_add_f32_e32 v174, v174, v175
	v_add_f32_e32 v19, v19, v172
	v_add_f32_e32 v0, v0, v174
	s_waitcnt vmcnt(10)
	v_lshlrev_b32_e32 v132, 16, v104
	v_and_b32_e32 v133, 0xffff0000, v104
	v_lshlrev_b32_e32 v134, 16, v105
	v_and_b32_e32 v135, 0xffff0000, v105
	v_lshlrev_b32_e32 v136, 16, v120
	v_and_b32_e32 v137, 0xffff0000, v120
	v_lshlrev_b32_e32 v138, 16, v121
	v_and_b32_e32 v139, 0xffff0000, v121
	s_waitcnt lgkmcnt(7)
	v_mul_f32_e32 v172, v141, v133
	v_mul_f32_e32 v174, v141, v137
	v_fmac_f32_e32 v172, v140, v132
	v_fmac_f32_e32 v174, v140, v136
	v_mul_f32_e32 v173, v143, v135
	v_mul_f32_e32 v175, v143, v139
	v_fmac_f32_e32 v173, v142, v134
	v_fmac_f32_e32 v175, v142, v138
	ds_read_b128 v[140:143], v3 offset:3072
	v_add_f32_e32 v172, v172, v173
	v_add_f32_e32 v174, v174, v175
	v_add_f32_e32 v80, v80, v172
	v_add_f32_e32 v81, v81, v174
	s_waitcnt lgkmcnt(7)
	v_mul_f32_e32 v172, v145, v133
	v_mul_f32_e32 v174, v145, v137
	v_fmac_f32_e32 v172, v144, v132
	v_fmac_f32_e32 v174, v144, v136
	v_mul_f32_e32 v173, v147, v135
	v_mul_f32_e32 v175, v147, v139
	v_fmac_f32_e32 v173, v146, v134
	v_fmac_f32_e32 v175, v146, v138
	ds_read_b128 v[144:147], v3 offset:11264
	v_add_f32_e32 v172, v172, v173
	v_add_f32_e32 v174, v174, v175
	v_add_f32_e32 v82, v82, v172
	v_add_f32_e32 v83, v83, v174
	s_waitcnt lgkmcnt(7)
	v_mul_f32_e32 v172, v149, v133
	v_mul_f32_e32 v174, v149, v137
	v_fmac_f32_e32 v172, v148, v132
	v_fmac_f32_e32 v174, v148, v136
	v_mul_f32_e32 v173, v151, v135
	v_mul_f32_e32 v175, v151, v139
	v_fmac_f32_e32 v173, v150, v134
	v_fmac_f32_e32 v175, v150, v138
	ds_read_b128 v[148:151], v3 offset:19456
	v_add_f32_e32 v172, v172, v173
	v_add_f32_e32 v174, v174, v175
	v_add_f32_e32 v84, v84, v172
	v_add_f32_e32 v85, v85, v174
	s_waitcnt lgkmcnt(7)
; __device__ __forceinline__ void logf_phase(const Args& a, int l, const u64* ssv, LAS unsigned char* lds, int gw, int NGW, int wave, int lane) {
;     ...
;         for (int j = 0; j < 8; ++j) { float s0 = 0.f, s1 = 0.f;
; #pragma unroll
;             for (int i = 0; i < 8; ++i) { const f32x4 w = wl[j * (DM / 4) + lane + 64 * i];
;                 s0 += (h0[i][0] * w[0] + h0[i][1] * w[1]) + (h0[i][2] * w[2] + h0[i][3] * w[3]);
;                 s1 += (h1[i][0] * w[0] + h1[i][1] * w[1]) + (h1[i][2] * w[2] + h1[i][3] * w[3]); }
;             sa[j] = s0; sb[j] = s1;
;             __builtin_amdgcn_sched_barrier(0); }
	v_mul_f32_e32 v172, v153, v133
	v_mul_f32_e32 v174, v153, v137
	v_fmac_f32_e32 v172, v152, v132
	v_fmac_f32_e32 v174, v152, v136
	v_mul_f32_e32 v173, v155, v135
	v_mul_f32_e32 v175, v155, v139
	v_fmac_f32_e32 v173, v154, v134
	v_fmac_f32_e32 v175, v154, v138
	ds_read_b128 v[152:155], v3 offset:27648
	v_add_f32_e32 v172, v172, v173
	v_add_f32_e32 v174, v174, v175
	v_add_f32_e32 v86, v86, v172
	v_add_f32_e32 v87, v87, v174
	s_waitcnt lgkmcnt(7)
	v_mul_f32_e32 v172, v157, v133
	v_mul_f32_e32 v174, v157, v137
	v_fmac_f32_e32 v172, v156, v132
	v_fmac_f32_e32 v174, v156, v136
	v_mul_f32_e32 v173, v159, v135
	v_mul_f32_e32 v175, v159, v139
	v_fmac_f32_e32 v173, v158, v134
	v_fmac_f32_e32 v175, v158, v138
	ds_read_b128 v[156:159], v3 offset:35840
	v_add_f32_e32 v172, v172, v173
	v_add_f32_e32 v174, v174, v175
	v_add_f32_e32 v88, v88, v172
	v_add_f32_e32 v89, v89, v174
	s_waitcnt lgkmcnt(7)
	v_mul_f32_e32 v172, v161, v133
	v_mul_f32_e32 v174, v161, v137
	v_fmac_f32_e32 v172, v160, v132
	v_fmac_f32_e32 v174, v160, v136
	v_mul_f32_e32 v173, v163, v135
	v_mul_f32_e32 v175, v163, v139
	v_fmac_f32_e32 v173, v162, v134
	v_fmac_f32_e32 v175, v162, v138
	ds_read_b128 v[160:163], v3 offset:44032
	v_add_f32_e32 v172, v172, v173
	v_add_f32_e32 v174, v174, v175
	v_add_f32_e32 v90, v90, v172
	v_add_f32_e32 v91, v91, v174
	s_waitcnt lgkmcnt(7)
	v_mul_f32_e32 v172, v165, v133
	v_mul_f32_e32 v174, v165, v137
	v_fmac_f32_e32 v172, v164, v132
	v_fmac_f32_e32 v174, v164, v136
	v_mul_f32_e32 v173, v167, v135
	v_mul_f32_e32 v175, v167, v139
	v_fmac_f32_e32 v173, v166, v134
	v_fmac_f32_e32 v175, v166, v138
	ds_read_b128 v[164:167], v3 offset:52224
	v_add_f32_e32 v172, v172, v173
	v_add_f32_e32 v174, v174, v175
	v_add_f32_e32 v92, v92, v172
	v_add_f32_e32 v93, v93, v174
	s_waitcnt lgkmcnt(7)
	v_mul_f32_e32 v172, v169, v133
	v_mul_f32_e32 v174, v169, v137
	v_fmac_f32_e32 v172, v168, v132
	v_fmac_f32_e32 v174, v168, v136
	v_mul_f32_e32 v173, v171, v135
	v_mul_f32_e32 v175, v171, v139
	v_fmac_f32_e32 v173, v170, v134
	v_fmac_f32_e32 v175, v170, v138
	ds_read_b128 v[168:171], v3 offset:60416
	v_add_f32_e32 v172, v172, v173
	v_add_f32_e32 v174, v174, v175
	v_add_f32_e32 v19, v19, v172
	v_add_f32_e32 v0, v0, v174
	s_waitcnt vmcnt(8)
	v_lshlrev_b32_e32 v132, 16, v106
	v_and_b32_e32 v133, 0xffff0000, v106
	v_lshlrev_b32_e32 v134, 16, v107
	v_and_b32_e32 v135, 0xffff0000, v107
	v_lshlrev_b32_e32 v136, 16, v122
	v_and_b32_e32 v137, 0xffff0000, v122
	v_lshlrev_b32_e32 v138, 16, v123
	v_and_b32_e32 v139, 0xffff0000, v123
	s_waitcnt lgkmcnt(7)
	v_mul_f32_e32 v172, v141, v133
	v_mul_f32_e32 v174, v141, v137
	v_fmac_f32_e32 v172, v140, v132
	v_fmac_f32_e32 v174, v140, v136
	v_mul_f32_e32 v173, v143, v135
	v_mul_f32_e32 v175, v143, v139
	v_fmac_f32_e32 v173, v142, v134
	v_fmac_f32_e32 v175, v142, v138
	ds_read_b128 v[140:143], v3 offset:4096
	v_add_f32_e32 v172, v172, v173
	v_add_f32_e32 v174, v174, v175
	v_add_f32_e32 v80, v80, v172
	v_add_f32_e32 v81, v81, v174
	s_waitcnt lgkmcnt(7)
	v_mul_f32_e32 v172, v145, v133
	v_mul_f32_e32 v174, v145, v137
	v_fmac_f32_e32 v172, v144, v132
	v_fmac_f32_e32 v174, v144, v136
	v_mul_f32_e32 v173, v147, v135
	v_mul_f32_e32 v175, v147, v139
	v_fmac_f32_e32 v173, v146, v134
	v_fmac_f32_e32 v175, v146, v138
	ds_read_b128 v[144:147], v3 offset:12288
	v_add_f32_e32 v172, v172, v173
	v_add_f32_e32 v174, v174, v175
	v_add_f32_e32 v82, v82, v172
	v_add_f32_e32 v83, v83, v174
	s_waitcnt lgkmcnt(7)
	v_mul_f32_e32 v172, v149, v133
	v_mul_f32_e32 v174, v149, v137
	v_fmac_f32_e32 v172, v148, v132
	v_fmac_f32_e32 v174, v148, v136
	v_mul_f32_e32 v173, v151, v135
	v_mul_f32_e32 v175, v151, v139
	v_fmac_f32_e32 v173, v150, v134
	v_fmac_f32_e32 v175, v150, v138
	ds_read_b128 v[148:151], v3 offset:20480
	v_add_f32_e32 v172, v172, v173
	v_add_f32_e32 v174, v174, v175
	v_add_f32_e32 v84, v84, v172
	v_add_f32_e32 v85, v85, v174
	s_waitcnt lgkmcnt(7)
	v_mul_f32_e32 v172, v153, v133
	v_mul_f32_e32 v174, v153, v137
	v_fmac_f32_e32 v172, v152, v132
	v_fmac_f32_e32 v174, v152, v136
	v_mul_f32_e32 v173, v155, v135
	v_mul_f32_e32 v175, v155, v139
	v_fmac_f32_e32 v173, v154, v134
	v_fmac_f32_e32 v175, v154, v138
	ds_read_b128 v[152:155], v3 offset:28672
	v_add_f32_e32 v172, v172, v173
	v_add_f32_e32 v174, v174, v175
	v_add_f32_e32 v86, v86, v172
	v_add_f32_e32 v87, v87, v174
	s_waitcnt lgkmcnt(7)
	v_mul_f32_e32 v172, v157, v133
	v_mul_f32_e32 v174, v157, v137
	v_fmac_f32_e32 v172, v156, v132
	v_fmac_f32_e32 v174, v156, v136
	v_mul_f32_e32 v173, v159, v135
	v_mul_f32_e32 v175, v159, v139
	v_fmac_f32_e32 v173, v158, v134
	v_fmac_f32_e32 v175, v158, v138
	ds_read_b128 v[156:159], v3 offset:36864
	v_add_f32_e32 v172, v172, v173
	v_add_f32_e32 v174, v174, v175
	v_add_f32_e32 v88, v88, v172
	v_add_f32_e32 v89, v89, v174
	s_waitcnt lgkmcnt(7)
	v_mul_f32_e32 v172, v161, v133
	v_mul_f32_e32 v174, v161, v137
	v_fmac_f32_e32 v172, v160, v132
	v_fmac_f32_e32 v174, v160, v136
	v_mul_f32_e32 v173, v163, v135
	v_mul_f32_e32 v175, v163, v139
	v_fmac_f32_e32 v173, v162, v134
	v_fmac_f32_e32 v175, v162, v138
	ds_read_b128 v[160:163], v3 offset:45056
	v_add_f32_e32 v172, v172, v173
	v_add_f32_e32 v174, v174, v175
	v_add_f32_e32 v90, v90, v172
	v_add_f32_e32 v91, v91, v174
	s_waitcnt lgkmcnt(7)
	v_mul_f32_e32 v172, v165, v133
	v_mul_f32_e32 v174, v165, v137
	v_fmac_f32_e32 v172, v164, v132
	v_fmac_f32_e32 v174, v164, v136
	v_mul_f32_e32 v173, v167, v135
	v_mul_f32_e32 v175, v167, v139
	v_fmac_f32_e32 v173, v166, v134
	v_fmac_f32_e32 v175, v166, v138
	ds_read_b128 v[164:167], v3 offset:53248
	v_add_f32_e32 v172, v172, v173
	v_add_f32_e32 v174, v174, v175
	v_add_f32_e32 v92, v92, v172
	v_add_f32_e32 v93, v93, v174
	s_waitcnt lgkmcnt(7)
; __device__ __forceinline__ void logf_phase(const Args& a, int l, const u64* ssv, LAS unsigned char* lds, int gw, int NGW, int wave, int lane) {
;     ...
;         for (int j = 0; j < 8; ++j) { float s0 = 0.f, s1 = 0.f;
; #pragma unroll
;             for (int i = 0; i < 8; ++i) { const f32x4 w = wl[j * (DM / 4) + lane + 64 * i];
;                 s0 += (h0[i][0] * w[0] + h0[i][1] * w[1]) + (h0[i][2] * w[2] + h0[i][3] * w[3]);
;                 s1 += (h1[i][0] * w[0] + h1[i][1] * w[1]) + (h1[i][2] * w[2] + h1[i][3] * w[3]); }
;             sa[j] = s0; sb[j] = s1;
;             __builtin_amdgcn_sched_barrier(0); }
	v_mul_f32_e32 v172, v169, v133
	v_mul_f32_e32 v174, v169, v137
	v_fmac_f32_e32 v172, v168, v132
	v_fmac_f32_e32 v174, v168, v136
	v_mul_f32_e32 v173, v171, v135
	v_mul_f32_e32 v175, v171, v139
	v_fmac_f32_e32 v173, v170, v134
	v_fmac_f32_e32 v175, v170, v138
	ds_read_b128 v[168:171], v3 offset:61440
	v_add_f32_e32 v172, v172, v173
	v_add_f32_e32 v174, v174, v175
	v_add_f32_e32 v19, v19, v172
	v_add_f32_e32 v0, v0, v174
	s_waitcnt vmcnt(6)
	v_lshlrev_b32_e32 v132, 16, v108
	v_and_b32_e32 v133, 0xffff0000, v108
	v_lshlrev_b32_e32 v134, 16, v109
	v_and_b32_e32 v135, 0xffff0000, v109
	v_lshlrev_b32_e32 v136, 16, v124
	v_and_b32_e32 v137, 0xffff0000, v124
	v_lshlrev_b32_e32 v138, 16, v125
	v_and_b32_e32 v139, 0xffff0000, v125
	s_waitcnt lgkmcnt(7)
	v_mul_f32_e32 v172, v141, v133
	v_mul_f32_e32 v174, v141, v137
	v_fmac_f32_e32 v172, v140, v132
	v_fmac_f32_e32 v174, v140, v136
	v_mul_f32_e32 v173, v143, v135
	v_mul_f32_e32 v175, v143, v139
	v_fmac_f32_e32 v173, v142, v134
	v_fmac_f32_e32 v175, v142, v138
	ds_read_b128 v[140:143], v3 offset:5120
	v_add_f32_e32 v172, v172, v173
	v_add_f32_e32 v174, v174, v175
	v_add_f32_e32 v80, v80, v172
	v_add_f32_e32 v81, v81, v174
	s_waitcnt lgkmcnt(7)
	v_mul_f32_e32 v172, v145, v133
	v_mul_f32_e32 v174, v145, v137
	v_fmac_f32_e32 v172, v144, v132
	v_fmac_f32_e32 v174, v144, v136
	v_mul_f32_e32 v173, v147, v135
	v_mul_f32_e32 v175, v147, v139
	v_fmac_f32_e32 v173, v146, v134
	v_fmac_f32_e32 v175, v146, v138
	ds_read_b128 v[144:147], v3 offset:13312
	v_add_f32_e32 v172, v172, v173
	v_add_f32_e32 v174, v174, v175
	v_add_f32_e32 v82, v82, v172
	v_add_f32_e32 v83, v83, v174
	s_waitcnt lgkmcnt(7)
	v_mul_f32_e32 v172, v149, v133
	v_mul_f32_e32 v174, v149, v137
	v_fmac_f32_e32 v172, v148, v132
	v_fmac_f32_e32 v174, v148, v136
	v_mul_f32_e32 v173, v151, v135
	v_mul_f32_e32 v175, v151, v139
	v_fmac_f32_e32 v173, v150, v134
	v_fmac_f32_e32 v175, v150, v138
	ds_read_b128 v[148:151], v3 offset:21504
	v_add_f32_e32 v172, v172, v173
	v_add_f32_e32 v174, v174, v175
	v_add_f32_e32 v84, v84, v172
	v_add_f32_e32 v85, v85, v174
	s_waitcnt lgkmcnt(7)
	v_mul_f32_e32 v172, v153, v133
	v_mul_f32_e32 v174, v153, v137
	v_fmac_f32_e32 v172, v152, v132
	v_fmac_f32_e32 v174, v152, v136
	v_mul_f32_e32 v173, v155, v135
	v_mul_f32_e32 v175, v155, v139
	v_fmac_f32_e32 v173, v154, v134
	v_fmac_f32_e32 v175, v154, v138
	ds_read_b128 v[152:155], v3 offset:29696
	v_add_f32_e32 v172, v172, v173
	v_add_f32_e32 v174, v174, v175
	v_add_f32_e32 v86, v86, v172
	v_add_f32_e32 v87, v87, v174
	s_waitcnt lgkmcnt(7)
	v_mul_f32_e32 v172, v157, v133
	v_mul_f32_e32 v174, v157, v137
	v_fmac_f32_e32 v172, v156, v132
	v_fmac_f32_e32 v174, v156, v136
	v_mul_f32_e32 v173, v159, v135
	v_mul_f32_e32 v175, v159, v139
	v_fmac_f32_e32 v173, v158, v134
	v_fmac_f32_e32 v175, v158, v138
	ds_read_b128 v[156:159], v3 offset:37888
	v_add_f32_e32 v172, v172, v173
	v_add_f32_e32 v174, v174, v175
	v_add_f32_e32 v88, v88, v172
	v_add_f32_e32 v89, v89, v174
	s_waitcnt lgkmcnt(7)
	v_mul_f32_e32 v172, v161, v133
	v_mul_f32_e32 v174, v161, v137
	v_fmac_f32_e32 v172, v160, v132
	v_fmac_f32_e32 v174, v160, v136
	v_mul_f32_e32 v173, v163, v135
	v_mul_f32_e32 v175, v163, v139
	v_fmac_f32_e32 v173, v162, v134
	v_fmac_f32_e32 v175, v162, v138
	ds_read_b128 v[160:163], v3 offset:46080
	v_add_f32_e32 v172, v172, v173
	v_add_f32_e32 v174, v174, v175
	v_add_f32_e32 v90, v90, v172
	v_add_f32_e32 v91, v91, v174
	s_waitcnt lgkmcnt(7)
	v_mul_f32_e32 v172, v165, v133
	v_mul_f32_e32 v174, v165, v137
	v_fmac_f32_e32 v172, v164, v132
	v_fmac_f32_e32 v174, v164, v136
	v_mul_f32_e32 v173, v167, v135
	v_mul_f32_e32 v175, v167, v139
	v_fmac_f32_e32 v173, v166, v134
	v_fmac_f32_e32 v175, v166, v138
	ds_read_b128 v[164:167], v3 offset:54272
	v_add_f32_e32 v172, v172, v173
	v_add_f32_e32 v174, v174, v175
	v_add_f32_e32 v92, v92, v172
	v_add_f32_e32 v93, v93, v174
	s_waitcnt lgkmcnt(7)
	v_mul_f32_e32 v172, v169, v133
	v_mul_f32_e32 v174, v169, v137
	v_fmac_f32_e32 v172, v168, v132
	v_fmac_f32_e32 v174, v168, v136
	v_mul_f32_e32 v173, v171, v135
	v_mul_f32_e32 v175, v171, v139
	v_fmac_f32_e32 v173, v170, v134
	v_fmac_f32_e32 v175, v170, v138
	ds_read_b128 v[168:171], v3 offset:62464
	v_add_f32_e32 v172, v172, v173
	v_add_f32_e32 v174, v174, v175
	v_add_f32_e32 v19, v19, v172
	v_add_f32_e32 v0, v0, v174
	s_waitcnt vmcnt(4)
	v_lshlrev_b32_e32 v132, 16, v110
	v_and_b32_e32 v133, 0xffff0000, v110
	v_lshlrev_b32_e32 v134, 16, v111
	v_and_b32_e32 v135, 0xffff0000, v111
	v_lshlrev_b32_e32 v136, 16, v126
	v_and_b32_e32 v137, 0xffff0000, v126
	v_lshlrev_b32_e32 v138, 16, v127
	v_and_b32_e32 v139, 0xffff0000, v127
	s_waitcnt lgkmcnt(7)
	v_mul_f32_e32 v172, v141, v133
	v_mul_f32_e32 v174, v141, v137
	v_fmac_f32_e32 v172, v140, v132
	v_fmac_f32_e32 v174, v140, v136
	v_mul_f32_e32 v173, v143, v135
	v_mul_f32_e32 v175, v143, v139
	v_fmac_f32_e32 v173, v142, v134
	v_fmac_f32_e32 v175, v142, v138
	ds_read_b128 v[140:143], v3 offset:6144
	v_add_f32_e32 v172, v172, v173
	v_add_f32_e32 v174, v174, v175
	v_add_f32_e32 v80, v80, v172
	v_add_f32_e32 v81, v81, v174
	s_waitcnt lgkmcnt(7)
	v_mul_f32_e32 v172, v145, v133
	v_mul_f32_e32 v174, v145, v137
	v_fmac_f32_e32 v172, v144, v132
	v_fmac_f32_e32 v174, v144, v136
	v_mul_f32_e32 v173, v147, v135
	v_mul_f32_e32 v175, v147, v139
	v_fmac_f32_e32 v173, v146, v134
	v_fmac_f32_e32 v175, v146, v138
	ds_read_b128 v[144:147], v3 offset:14336
	v_add_f32_e32 v172, v172, v173
	v_add_f32_e32 v174, v174, v175
	v_add_f32_e32 v82, v82, v172
	v_add_f32_e32 v83, v83, v174
	s_waitcnt lgkmcnt(7)
; __device__ __forceinline__ void logf_phase(const Args& a, int l, const u64* ssv, LAS unsigned char* lds, int gw, int NGW, int wave, int lane) {
;     ...
;         for (int j = 0; j < 8; ++j) { float s0 = 0.f, s1 = 0.f;
; #pragma unroll
;             for (int i = 0; i < 8; ++i) { const f32x4 w = wl[j * (DM / 4) + lane + 64 * i];
;                 s0 += (h0[i][0] * w[0] + h0[i][1] * w[1]) + (h0[i][2] * w[2] + h0[i][3] * w[3]);
;                 s1 += (h1[i][0] * w[0] + h1[i][1] * w[1]) + (h1[i][2] * w[2] + h1[i][3] * w[3]); }
;             sa[j] = s0; sb[j] = s1;
;             __builtin_amdgcn_sched_barrier(0); }
	v_mul_f32_e32 v172, v149, v133
	v_mul_f32_e32 v174, v149, v137
	v_fmac_f32_e32 v172, v148, v132
	v_fmac_f32_e32 v174, v148, v136
	v_mul_f32_e32 v173, v151, v135
	v_mul_f32_e32 v175, v151, v139
	v_fmac_f32_e32 v173, v150, v134
	v_fmac_f32_e32 v175, v150, v138
	ds_read_b128 v[148:151], v3 offset:22528
	v_add_f32_e32 v172, v172, v173
	v_add_f32_e32 v174, v174, v175
	v_add_f32_e32 v84, v84, v172
	v_add_f32_e32 v85, v85, v174
	s_waitcnt lgkmcnt(7)
	v_mul_f32_e32 v172, v153, v133
	v_mul_f32_e32 v174, v153, v137
	v_fmac_f32_e32 v172, v152, v132
	v_fmac_f32_e32 v174, v152, v136
	v_mul_f32_e32 v173, v155, v135
	v_mul_f32_e32 v175, v155, v139
	v_fmac_f32_e32 v173, v154, v134
	v_fmac_f32_e32 v175, v154, v138
	ds_read_b128 v[152:155], v3 offset:30720
	v_add_f32_e32 v172, v172, v173
	v_add_f32_e32 v174, v174, v175
	v_add_f32_e32 v86, v86, v172
	v_add_f32_e32 v87, v87, v174
	s_waitcnt lgkmcnt(7)
	v_mul_f32_e32 v172, v157, v133
	v_mul_f32_e32 v174, v157, v137
	v_fmac_f32_e32 v172, v156, v132
	v_fmac_f32_e32 v174, v156, v136
	v_mul_f32_e32 v173, v159, v135
	v_mul_f32_e32 v175, v159, v139
	v_fmac_f32_e32 v173, v158, v134
	v_fmac_f32_e32 v175, v158, v138
	ds_read_b128 v[156:159], v3 offset:38912
	v_add_f32_e32 v172, v172, v173
	v_add_f32_e32 v174, v174, v175
	v_add_f32_e32 v88, v88, v172
	v_add_f32_e32 v89, v89, v174
	s_waitcnt lgkmcnt(7)
	v_mul_f32_e32 v172, v161, v133
	v_mul_f32_e32 v174, v161, v137
	v_fmac_f32_e32 v172, v160, v132
	v_fmac_f32_e32 v174, v160, v136
	v_mul_f32_e32 v173, v163, v135
	v_mul_f32_e32 v175, v163, v139
	v_fmac_f32_e32 v173, v162, v134
	v_fmac_f32_e32 v175, v162, v138
	ds_read_b128 v[160:163], v3 offset:47104
	v_add_f32_e32 v172, v172, v173
	v_add_f32_e32 v174, v174, v175
	v_add_f32_e32 v90, v90, v172
	v_add_f32_e32 v91, v91, v174
	s_waitcnt lgkmcnt(7)
	v_mul_f32_e32 v172, v165, v133
	v_mul_f32_e32 v174, v165, v137
	v_fmac_f32_e32 v172, v164, v132
	v_fmac_f32_e32 v174, v164, v136
	v_mul_f32_e32 v173, v167, v135
	v_mul_f32_e32 v175, v167, v139
	v_fmac_f32_e32 v173, v166, v134
	v_fmac_f32_e32 v175, v166, v138
	ds_read_b128 v[164:167], v3 offset:55296
	v_add_f32_e32 v172, v172, v173
	v_add_f32_e32 v174, v174, v175
	v_add_f32_e32 v92, v92, v172
	v_add_f32_e32 v93, v93, v174
	s_waitcnt lgkmcnt(7)
	v_mul_f32_e32 v172, v169, v133
	v_mul_f32_e32 v174, v169, v137
	v_fmac_f32_e32 v172, v168, v132
	v_fmac_f32_e32 v174, v168, v136
	v_mul_f32_e32 v173, v171, v135
	v_mul_f32_e32 v175, v171, v139
	v_fmac_f32_e32 v173, v170, v134
	v_fmac_f32_e32 v175, v170, v138
	ds_read_b128 v[168:171], v3 offset:63488
	v_add_f32_e32 v172, v172, v173
	v_add_f32_e32 v174, v174, v175
	v_add_f32_e32 v19, v19, v172
	v_add_f32_e32 v0, v0, v174
	s_waitcnt vmcnt(2)
	v_lshlrev_b32_e32 v132, 16, v112
	v_and_b32_e32 v133, 0xffff0000, v112
	v_lshlrev_b32_e32 v134, 16, v113
	v_and_b32_e32 v135, 0xffff0000, v113
	v_lshlrev_b32_e32 v136, 16, v128
	v_and_b32_e32 v137, 0xffff0000, v128
	v_lshlrev_b32_e32 v138, 16, v129
	v_and_b32_e32 v139, 0xffff0000, v129
	s_waitcnt lgkmcnt(7)
	v_mul_f32_e32 v172, v141, v133
	v_mul_f32_e32 v174, v141, v137
	v_fmac_f32_e32 v172, v140, v132
	v_fmac_f32_e32 v174, v140, v136
	v_mul_f32_e32 v173, v143, v135
	v_mul_f32_e32 v175, v143, v139
	v_fmac_f32_e32 v173, v142, v134
	v_fmac_f32_e32 v175, v142, v138
	ds_read_b128 v[140:143], v3 offset:7168
	v_add_f32_e32 v172, v172, v173
	v_add_f32_e32 v174, v174, v175
	v_add_f32_e32 v80, v80, v172
	v_add_f32_e32 v81, v81, v174
	s_waitcnt lgkmcnt(7)
	v_mul_f32_e32 v172, v145, v133
	v_mul_f32_e32 v174, v145, v137
	v_fmac_f32_e32 v172, v144, v132
	v_fmac_f32_e32 v174, v144, v136
	v_mul_f32_e32 v173, v147, v135
	v_mul_f32_e32 v175, v147, v139
	v_fmac_f32_e32 v173, v146, v134
	v_fmac_f32_e32 v175, v146, v138
	ds_read_b128 v[144:147], v3 offset:15360
	v_add_f32_e32 v172, v172, v173
	v_add_f32_e32 v174, v174, v175
	v_add_f32_e32 v82, v82, v172
	v_add_f32_e32 v83, v83, v174
	s_waitcnt lgkmcnt(7)
	v_mul_f32_e32 v172, v149, v133
	v_mul_f32_e32 v174, v149, v137
	v_fmac_f32_e32 v172, v148, v132
	v_fmac_f32_e32 v174, v148, v136
	v_mul_f32_e32 v173, v151, v135
	v_mul_f32_e32 v175, v151, v139
	v_fmac_f32_e32 v173, v150, v134
	v_fmac_f32_e32 v175, v150, v138
	ds_read_b128 v[148:151], v3 offset:23552
	v_add_f32_e32 v172, v172, v173
	v_add_f32_e32 v174, v174, v175
	v_add_f32_e32 v84, v84, v172
	v_add_f32_e32 v85, v85, v174
	s_waitcnt lgkmcnt(7)
	v_mul_f32_e32 v172, v153, v133
	v_mul_f32_e32 v174, v153, v137
	v_fmac_f32_e32 v172, v152, v132
	v_fmac_f32_e32 v174, v152, v136
	v_mul_f32_e32 v173, v155, v135
	v_mul_f32_e32 v175, v155, v139
	v_fmac_f32_e32 v173, v154, v134
	v_fmac_f32_e32 v175, v154, v138
	ds_read_b128 v[152:155], v3 offset:31744
	v_add_f32_e32 v172, v172, v173
	v_add_f32_e32 v174, v174, v175
	v_add_f32_e32 v86, v86, v172
	v_add_f32_e32 v87, v87, v174
	s_waitcnt lgkmcnt(7)
	v_mul_f32_e32 v172, v157, v133
	v_mul_f32_e32 v174, v157, v137
	v_fmac_f32_e32 v172, v156, v132
	v_fmac_f32_e32 v174, v156, v136
	v_mul_f32_e32 v173, v159, v135
	v_mul_f32_e32 v175, v159, v139
	v_fmac_f32_e32 v173, v158, v134
	v_fmac_f32_e32 v175, v158, v138
	ds_read_b128 v[156:159], v3 offset:39936
	v_add_f32_e32 v172, v172, v173
	v_add_f32_e32 v174, v174, v175
	v_add_f32_e32 v88, v88, v172
	v_add_f32_e32 v89, v89, v174
	s_waitcnt lgkmcnt(7)
	v_mul_f32_e32 v172, v161, v133
	v_mul_f32_e32 v174, v161, v137
	v_fmac_f32_e32 v172, v160, v132
	v_fmac_f32_e32 v174, v160, v136
	v_mul_f32_e32 v173, v163, v135
	v_mul_f32_e32 v175, v163, v139
	v_fmac_f32_e32 v173, v162, v134
	v_fmac_f32_e32 v175, v162, v138
	ds_read_b128 v[160:163], v3 offset:48128
	v_add_f32_e32 v172, v172, v173
	v_add_f32_e32 v174, v174, v175
	v_add_f32_e32 v90, v90, v172
	v_add_f32_e32 v91, v91, v174
	s_waitcnt lgkmcnt(7)
; __device__ __forceinline__ void logf_phase(const Args& a, int l, const u64* ssv, LAS unsigned char* lds, int gw, int NGW, int wave, int lane) {
;     ...
;         for (int j = 0; j < 8; ++j) { float s0 = 0.f, s1 = 0.f;
; #pragma unroll
;             for (int i = 0; i < 8; ++i) { const f32x4 w = wl[j * (DM / 4) + lane + 64 * i];
;                 s0 += (h0[i][0] * w[0] + h0[i][1] * w[1]) + (h0[i][2] * w[2] + h0[i][3] * w[3]);
;                 s1 += (h1[i][0] * w[0] + h1[i][1] * w[1]) + (h1[i][2] * w[2] + h1[i][3] * w[3]); }
;             sa[j] = s0; sb[j] = s1;
;             __builtin_amdgcn_sched_barrier(0); }
;         float f0, f1;
;         { const bool b0 = lane & 1, b1 = lane & 2, b2 = lane & 4;
;           float ta[4], tb[4];
; #pragma unroll
;           for (int k = 0; k < 4; ++k) { const float ka = b0 ? sa[2 * k + 1] : sa[2 * k], xa = b0 ? sa[2 * k] : sa[2 * k + 1]; ta[k] = ka + __shfl_xor(xa, 1);
;                                         const float kb = b0 ? sb[2 * k + 1] : sb[2 * k], xb = b0 ? sb[2 * k] : sb[2 * k + 1]; tb[k] = kb + __shfl_xor(xb, 1); }
;           float ua[2], ub[2];
; #pragma unroll
;           for (int k = 0; k < 2; ++k) { const float ka = b1 ? ta[2 * k + 1] : ta[2 * k], xa = b1 ? ta[2 * k] : ta[2 * k + 1]; ua[k] = ka + __shfl_xor(xa, 2);
;                                         const float kb = b1 ? tb[2 * k + 1] : tb[2 * k], xb = b1 ? tb[2 * k] : tb[2 * k + 1]; ub[k] = kb + __shfl_xor(xb, 2); }
;           { const float ka = b2 ? ua[1] : ua[0], xa = b2 ? ua[0] : ua[1]; f0 = ka + __shfl_xor(xa, 4);
;             const float kb = b2 ? ub[1] : ub[0], xb = b2 ? ub[0] : ub[1]; f1 = kb + __shfl_xor(xb, 4); }
;           f0 += __shfl_xor(f0, 8); f0 += __shfl_xor(f0, 16); f0 += __shfl_xor(f0, 32);
;           f1 += __shfl_xor(f1, 8); f1 += __shfl_xor(f1, 16); f1 += __shfl_xor(f1, 32); }
	v_mul_f32_e32 v172, v165, v133
	v_mul_f32_e32 v174, v165, v137
	v_fmac_f32_e32 v172, v164, v132
	v_fmac_f32_e32 v174, v164, v136
	v_mul_f32_e32 v173, v167, v135
	v_mul_f32_e32 v175, v167, v139
	v_fmac_f32_e32 v173, v166, v134
	v_fmac_f32_e32 v175, v166, v138
	ds_read_b128 v[164:167], v3 offset:56320
	v_add_f32_e32 v172, v172, v173
	v_add_f32_e32 v174, v174, v175
	v_add_f32_e32 v92, v92, v172
	v_add_f32_e32 v93, v93, v174
	s_waitcnt lgkmcnt(7)
	v_mul_f32_e32 v172, v169, v133
	v_mul_f32_e32 v174, v169, v137
	v_fmac_f32_e32 v172, v168, v132
	v_fmac_f32_e32 v174, v168, v136
	v_mul_f32_e32 v173, v171, v135
	v_mul_f32_e32 v175, v171, v139
	v_fmac_f32_e32 v173, v170, v134
	v_fmac_f32_e32 v175, v170, v138
	ds_read_b128 v[168:171], v3 offset:64512
	v_add_f32_e32 v172, v172, v173
	v_add_f32_e32 v174, v174, v175
	v_add_f32_e32 v19, v19, v172
	v_add_f32_e32 v0, v0, v174
	s_waitcnt vmcnt(0)
	v_lshlrev_b32_e32 v132, 16, v114
	v_and_b32_e32 v133, 0xffff0000, v114
	v_lshlrev_b32_e32 v134, 16, v115
	v_and_b32_e32 v135, 0xffff0000, v115
	v_lshlrev_b32_e32 v136, 16, v130
	v_and_b32_e32 v137, 0xffff0000, v130
	v_lshlrev_b32_e32 v138, 16, v131
	v_and_b32_e32 v139, 0xffff0000, v131
	s_waitcnt lgkmcnt(7)
	v_mul_f32_e32 v172, v141, v133
	v_mul_f32_e32 v174, v141, v137
	v_fmac_f32_e32 v172, v140, v132
	v_fmac_f32_e32 v174, v140, v136
	v_mul_f32_e32 v173, v143, v135
	v_mul_f32_e32 v175, v143, v139
	v_fmac_f32_e32 v173, v142, v134
	v_fmac_f32_e32 v175, v142, v138
	v_add_f32_e32 v172, v172, v173
	v_add_f32_e32 v174, v174, v175
	v_add_f32_e32 v80, v80, v172
	v_add_f32_e32 v81, v81, v174
	s_waitcnt lgkmcnt(6)
	v_mul_f32_e32 v172, v145, v133
	v_mul_f32_e32 v174, v145, v137
	v_fmac_f32_e32 v172, v144, v132
	v_fmac_f32_e32 v174, v144, v136
	v_mul_f32_e32 v173, v147, v135
	v_mul_f32_e32 v175, v147, v139
	v_fmac_f32_e32 v173, v146, v134
	v_fmac_f32_e32 v175, v146, v138
	v_add_f32_e32 v172, v172, v173
	v_add_f32_e32 v174, v174, v175
	v_add_f32_e32 v82, v82, v172
	v_add_f32_e32 v83, v83, v174
	s_waitcnt lgkmcnt(5)
	v_mul_f32_e32 v172, v149, v133
	v_mul_f32_e32 v174, v149, v137
	v_fmac_f32_e32 v172, v148, v132
	v_fmac_f32_e32 v174, v148, v136
	v_mul_f32_e32 v173, v151, v135
	v_mul_f32_e32 v175, v151, v139
	v_fmac_f32_e32 v173, v150, v134
	v_fmac_f32_e32 v175, v150, v138
	v_add_f32_e32 v172, v172, v173
	v_add_f32_e32 v174, v174, v175
	v_add_f32_e32 v84, v84, v172
	v_add_f32_e32 v85, v85, v174
	s_waitcnt lgkmcnt(4)
	v_mul_f32_e32 v172, v153, v133
	v_mul_f32_e32 v174, v153, v137
	v_fmac_f32_e32 v172, v152, v132
	v_fmac_f32_e32 v174, v152, v136
	v_mul_f32_e32 v173, v155, v135
	v_mul_f32_e32 v175, v155, v139
	v_fmac_f32_e32 v173, v154, v134
	v_fmac_f32_e32 v175, v154, v138
	v_add_f32_e32 v172, v172, v173
	v_add_f32_e32 v174, v174, v175
	v_add_f32_e32 v86, v86, v172
	v_add_f32_e32 v87, v87, v174
	s_waitcnt lgkmcnt(3)
	v_mul_f32_e32 v172, v157, v133
	v_mul_f32_e32 v174, v157, v137
	v_fmac_f32_e32 v172, v156, v132
	v_fmac_f32_e32 v174, v156, v136
	v_mul_f32_e32 v173, v159, v135
	v_mul_f32_e32 v175, v159, v139
	v_fmac_f32_e32 v173, v158, v134
	v_fmac_f32_e32 v175, v158, v138
	v_add_f32_e32 v172, v172, v173
	v_add_f32_e32 v174, v174, v175
	v_add_f32_e32 v88, v88, v172
	v_add_f32_e32 v89, v89, v174
	s_waitcnt lgkmcnt(2)
	v_mul_f32_e32 v172, v161, v133
	v_mul_f32_e32 v174, v161, v137
	v_fmac_f32_e32 v172, v160, v132
	v_fmac_f32_e32 v174, v160, v136
	v_mul_f32_e32 v173, v163, v135
	v_mul_f32_e32 v175, v163, v139
	v_fmac_f32_e32 v173, v162, v134
	v_fmac_f32_e32 v175, v162, v138
	v_add_f32_e32 v172, v172, v173
	v_add_f32_e32 v174, v174, v175
	v_add_f32_e32 v90, v90, v172
	v_add_f32_e32 v91, v91, v174
	s_waitcnt lgkmcnt(1)
	v_mul_f32_e32 v172, v165, v133
	v_mul_f32_e32 v174, v165, v137
	v_fmac_f32_e32 v172, v164, v132
	v_fmac_f32_e32 v174, v164, v136
	v_mul_f32_e32 v173, v167, v135
	v_mul_f32_e32 v175, v167, v139
	v_fmac_f32_e32 v173, v166, v134
	v_fmac_f32_e32 v175, v166, v138
	v_add_f32_e32 v172, v172, v173
	v_add_f32_e32 v174, v174, v175
	v_add_f32_e32 v92, v92, v172
	v_add_f32_e32 v93, v93, v174
	s_waitcnt lgkmcnt(0)
	v_mul_f32_e32 v172, v169, v133
	v_mul_f32_e32 v174, v169, v137
	v_fmac_f32_e32 v172, v168, v132
	v_fmac_f32_e32 v174, v168, v136
	v_mul_f32_e32 v173, v171, v135
	v_mul_f32_e32 v175, v171, v139
	v_fmac_f32_e32 v173, v170, v134
	v_fmac_f32_e32 v175, v170, v138
	v_add_f32_e32 v172, v172, v173
	v_add_f32_e32 v174, v174, v175
	v_add_f32_e32 v19, v19, v172
	v_add_f32_e32 v0, v0, v174
	v_cndmask_b32_e64 v10, v80, v82, s[36:37]
	ds_bpermute_b32 v10, v13, v10
	v_cndmask_b32_e64 v11, v82, v80, s[36:37]
	v_cndmask_b32_e64 v20, v81, v83, s[36:37]
	ds_bpermute_b32 v20, v13, v20
	v_cndmask_b32_e64 v22, v85, v87, s[36:37]
	s_waitcnt lgkmcnt(1)
	v_add_f32_e32 v10, v11, v10
	v_cndmask_b32_e64 v11, v84, v86, s[36:37]
	ds_bpermute_b32 v11, v13, v11
	ds_bpermute_b32 v22, v13, v22
	v_cndmask_b32_e64 v23, v88, v90, s[36:37]
	ds_bpermute_b32 v23, v13, v23
	v_cndmask_b32_e64 v24, v89, v91, s[36:37]
	v_cndmask_b32_e64 v21, v83, v81, s[36:37]
	ds_bpermute_b32 v24, v13, v24
	v_cndmask_b32_e64 v25, v92, v19, s[36:37]
	s_waitcnt lgkmcnt(4)
	v_add_f32_e32 v20, v21, v20
	v_cndmask_b32_e64 v21, v86, v84, s[36:37]
	ds_bpermute_b32 v25, v13, v25
	s_waitcnt lgkmcnt(4)
	v_add_f32_e32 v11, v21, v11
	v_cndmask_b32_e64 v21, v87, v85, s[36:37]
	s_waitcnt lgkmcnt(3)
	v_add_f32_e32 v21, v21, v22
	v_cndmask_b32_e64 v22, v90, v88, s[36:37]
	s_waitcnt lgkmcnt(2)
	v_add_f32_e32 v22, v22, v23
	v_cndmask_b32_e64 v23, v91, v89, s[36:37]
	s_waitcnt lgkmcnt(1)
	v_add_f32_e32 v23, v23, v24
	v_cndmask_b32_e64 v19, v19, v92, s[36:37]
	v_cndmask_b32_e64 v24, v93, v0, s[36:37]
	ds_bpermute_b32 v24, v13, v24
	s_waitcnt lgkmcnt(1)
; __device__ __forceinline__ float rstd_of(u64 ss) { return rsqrtf((float)ss * (1.0f / 4294967296.0f) * (1.0f / DM) + EPS); }
; __device__ __forceinline__ void logf_phase(const Args& a, int l, const u64* ssv, LAS unsigned char* lds, int gw, int NGW, int wave, int lane) {
;     ...
;         { const bool b0 = lane & 1, b1 = lane & 2, b2 = lane & 4;
;           float ta[4], tb[4];
; #pragma unroll
;           for (int k = 0; k < 4; ++k) { const float ka = b0 ? sa[2 * k + 1] : sa[2 * k], xa = b0 ? sa[2 * k] : sa[2 * k + 1]; ta[k] = ka + __shfl_xor(xa, 1);
;                                         const float kb = b0 ? sb[2 * k + 1] : sb[2 * k], xb = b0 ? sb[2 * k] : sb[2 * k + 1]; tb[k] = kb + __shfl_xor(xb, 1); }
;           float ua[2], ub[2];
; #pragma unroll
;           for (int k = 0; k < 2; ++k) { const float ka = b1 ? ta[2 * k + 1] : ta[2 * k], xa = b1 ? ta[2 * k] : ta[2 * k + 1]; ua[k] = ka + __shfl_xor(xa, 2);
;                                         const float kb = b1 ? tb[2 * k + 1] : tb[2 * k], xb = b1 ? tb[2 * k] : tb[2 * k + 1]; ub[k] = kb + __shfl_xor(xb, 2); }
;           { const float ka = b2 ? ua[1] : ua[0], xa = b2 ? ua[0] : ua[1]; f0 = ka + __shfl_xor(xa, 4);
;             const float kb = b2 ? ub[1] : ub[0], xb = b2 ? ub[0] : ub[1]; f1 = kb + __shfl_xor(xb, 4); }
;           f0 += __shfl_xor(f0, 8); f0 += __shfl_xor(f0, 16); f0 += __shfl_xor(f0, 32);
;           f1 += __shfl_xor(f1, 8); f1 += __shfl_xor(f1, 16); f1 += __shfl_xor(f1, 32); }
;         const int r = (lane & 8) ? r1 : r0; const float fsel = (lane & 8) ? f1 : f0;
;         const float xv = fsel * rstd_of(ssv[r]) + a.b_forget[l * 8 + (lane & 7)];
;         const float lf = fminf(xv, 0.f) - log1pf(expf(-fabsf(xv)));
;         if (lane < 16) {
	v_add_f32_e32 v19, v19, v25
	v_cndmask_b32_e64 v25, v10, v11, s[38:39]
	v_cndmask_b32_e64 v10, v11, v10, s[38:39]
	v_cndmask_b32_e64 v11, v20, v21, s[38:39]
	ds_bpermute_b32 v11, v14, v11
	v_cndmask_b32_e64 v0, v0, v93, s[36:37]
	s_waitcnt lgkmcnt(1)
	v_add_f32_e32 v0, v0, v24
	v_cndmask_b32_e64 v20, v21, v20, s[38:39]
	v_cndmask_b32_e64 v21, v22, v19, s[38:39]
	s_waitcnt lgkmcnt(0)
	v_add_f32_e32 v11, v20, v11
	v_cndmask_b32_e64 v20, v23, v0, s[38:39]
	ds_bpermute_b32 v25, v14, v25
	ds_bpermute_b32 v21, v14, v21
	ds_bpermute_b32 v20, v14, v20
	v_cndmask_b32_e64 v19, v19, v22, s[38:39]
	v_cndmask_b32_e64 v0, v0, v23, s[38:39]
	s_waitcnt lgkmcnt(2)
	v_add_f32_e32 v10, v10, v25
	s_waitcnt lgkmcnt(1)
	v_add_f32_e32 v19, v19, v21
	s_waitcnt lgkmcnt(0)
	v_add_f32_e32 v0, v0, v20
	v_cndmask_b32_e64 v21, v10, v19, s[40:41]
	v_cndmask_b32_e64 v20, v11, v0, s[40:41]
	ds_bpermute_b32 v21, v15, v21
	ds_bpermute_b32 v20, v15, v20
	v_cndmask_b32_e64 v10, v19, v10, s[40:41]
	v_cndmask_b32_e64 v0, v0, v11, s[40:41]
	s_waitcnt lgkmcnt(1)
	v_add_f32_e32 v10, v10, v21
	s_waitcnt lgkmcnt(0)
	v_add_f32_e32 v0, v0, v20
	ds_bpermute_b32 v11, v16, v10
	ds_bpermute_b32 v19, v16, v0
	s_waitcnt lgkmcnt(1)
	v_add_f32_e32 v10, v10, v11
	s_waitcnt lgkmcnt(0)
	v_add_f32_e32 v19, v0, v19
	ds_bpermute_b32 v11, v17, v10
	ds_bpermute_b32 v20, v17, v19
	s_waitcnt lgkmcnt(1)
	v_add_f32_e32 v0, v10, v11
	s_waitcnt lgkmcnt(0)
	v_add_f32_e32 v11, v19, v20
	ds_bpermute_b32 v10, v18, v0
	ds_bpermute_b32 v19, v18, v11
	s_and_saveexec_b64 s[16:17], s[44:45]
	s_cbranch_execz .LBB0_336
; __device__ __forceinline__ float rstd_of(u64 ss) { return rsqrtf((float)ss * (1.0f / 4294967296.0f) * (1.0f / DM) + EPS); }
; __device__ __forceinline__ void logf_phase(const Args& a, int l, const u64* ssv, LAS unsigned char* lds, int gw, int NGW, int wave, int lane) {
;     ...
;         const int r = (lane & 8) ? r1 : r0; const float fsel = (lane & 8) ? f1 : f0;
;         const float xv = fsel * rstd_of(ssv[r]) + a.b_forget[l * 8 + (lane & 7)];
;         const float lf = fminf(xv, 0.f) - log1pf(expf(-fabsf(xv)));
;         if (lane < 16) {
;             if (r < MX) { const int b = r >> 12, sq = r & 4095; logf[((size_t)b * 8 + (lane & 7)) * LKV + NMETA + sq] = lf; }
;             else { for (int bb = 0; bb < NB; ++bb) logf[((size_t)bb * 8 + (lane & 7)) * LKV + (r - MX)] = lf; }
	s_add_i32 s1, s0, 1
	s_waitcnt lgkmcnt(1)
	v_add_f32_e32 v0, v0, v10
	s_waitcnt lgkmcnt(0)
	v_add_f32_e32 v11, v11, v19
	v_mov_b32_e32 v10, s1
	v_mov_b32_e32 v19, s0
	v_cndmask_b32_e64 v10, v10, v19, s[42:43]
	v_cndmask_b32_e64 v0, v11, v0, s[42:43]
	v_ashrrev_i32_e32 v11, 31, v10
	v_lshl_add_u64 v[20:21], v[10:11], 3, s[4:5]
	global_load_dwordx2 v[20:21], v[20:21], off
	s_mov_b32 s1, 0xbfb8aa3b
	s_waitcnt vmcnt(0)
	v_ffbh_u32_e32 v11, v21
	v_min_u32_e32 v11, 32, v11
	v_lshlrev_b64 v[20:21], v11, v[20:21]
	v_min_u32_e32 v19, 1, v20
	v_or_b32_e32 v19, v21, v19
	v_cvt_f32_u32_e32 v19, v19
	v_sub_u32_e32 v11, 32, v11
	v_ldexp_f32 v11, v19, v11
	v_mul_f32_e32 v11, 0x2f800000, v11
	v_fmamk_f32 v11, v11, 0x3a000000, v238
	v_cmp_gt_f32_e32 vcc, s34, v11
	v_mul_f32_e32 v19, 0x4b800000, v11
	s_nop 0
	v_cndmask_b32_e32 v11, v11, v19, vcc
	v_rsq_f32_e32 v11, v11
	s_nop 0
	v_mul_f32_e32 v19, 0x45800000, v11
	v_cndmask_b32_e32 v11, v11, v19, vcc
	global_load_dword v19, v[4:5], off
	s_waitcnt vmcnt(0)
	v_fmac_f32_e32 v19, v0, v11
	v_mul_f32_e64 v11, |v19|, s1
	v_fma_f32 v20, |v19|, s1, -v11
	s_mov_b32 s1, 0xb2a5705f
	v_rndne_f32_e32 v21, v11
	v_fma_f32 v20, |v19|, s1, v20
	v_sub_f32_e32 v11, v11, v21
	v_add_f32_e32 v11, v11, v20
	v_exp_f32_e32 v11, v11
	v_cvt_i32_f32_e32 v20, v21
	s_mov_b32 s1, 0x42ce8ed0
	v_cmp_ngt_f32_e64 vcc, |v19|, s1
	s_mov_b32 s1, 0xc2b17218
	v_ldexp_f32 v11, v11, v20
	v_cndmask_b32_e32 v11, 0, v11, vcc
	v_cmp_nlt_f32_e64 vcc, |v19|, s1
	v_min_f32_e32 v0, 0, v19
	s_mov_b32 s1, 0x3f2aaaab
	v_cndmask_b32_e32 v11, v228, v11, vcc
	v_add_f32_e32 v19, 1.0, v11
	v_add_f32_e32 v20, -1.0, v19
	v_sub_f32_e32 v21, v20, v19
	v_add_f32_e32 v21, 1.0, v21
	v_sub_f32_e32 v20, v11, v20
	v_add_f32_e32 v22, v20, v21
	v_frexp_mant_f32_e32 v20, v19
	v_cmp_gt_f32_e32 vcc, s1, v20
	v_cvt_f64_f32_e32 v[20:21], v19
	v_frexp_exp_i32_f64_e32 v20, v[20:21]
	v_subbrev_co_u32_e32 v20, vcc, 0, v20, vcc
	v_sub_u32_e32 v21, 0, v20
	v_ldexp_f32 v19, v19, v21
	v_ldexp_f32 v21, v22, v21
	v_add_f32_e32 v22, -1.0, v19
	v_add_f32_e32 v23, 1.0, v22
	v_sub_f32_e32 v23, v19, v23
	v_add_f32_e32 v23, v21, v23
	v_add_f32_e32 v24, v22, v23
	v_sub_f32_e32 v22, v22, v24
	v_add_f32_e32 v22, v23, v22
	v_add_f32_e32 v23, 1.0, v19
	v_add_f32_e32 v25, -1.0, v23
	v_sub_f32_e32 v19, v19, v25
	v_add_f32_e32 v19, v21, v19
	v_add_f32_e32 v21, v23, v19
	v_sub_f32_e32 v23, v23, v21
	v_add_f32_e32 v19, v19, v23
	v_rcp_f32_e32 v23, v21
	v_cvt_f32_i32_e32 v20, v20
	s_mov_b32 s1, 0x3f317218
	v_mul_f32_e32 v25, v24, v23
	v_mul_f32_e32 v26, v21, v25
	v_fma_f32 v27, v25, v21, -v26
	v_fmac_f32_e32 v27, v25, v19
	v_add_f32_e32 v28, v26, v27
	v_sub_f32_e32 v29, v24, v28
	v_sub_f32_e32 v24, v24, v29
	v_sub_f32_e32 v26, v28, v26
	v_sub_f32_e32 v24, v24, v28
	v_add_f32_e32 v22, v22, v24
	v_sub_f32_e32 v24, v26, v27
	v_add_f32_e32 v22, v24, v22
	v_add_f32_e32 v24, v29, v22
	v_mul_f32_e32 v26, v23, v24
	v_mul_f32_e32 v27, v21, v26
	v_fma_f32 v21, v26, v21, -v27
	v_fmac_f32_e32 v21, v26, v19
	v_sub_f32_e32 v19, v29, v24
	v_add_f32_e32 v19, v22, v19
	v_add_f32_e32 v22, v27, v21
	v_sub_f32_e32 v28, v24, v22
	v_sub_f32_e32 v24, v24, v28
	v_sub_f32_e32 v27, v22, v27
	v_sub_f32_e32 v22, v24, v22
	v_add_f32_e32 v19, v19, v22
	v_sub_f32_e32 v21, v27, v21
	v_add_f32_e32 v19, v21, v19
	v_add_f32_e32 v21, v25, v26
	v_add_f32_e32 v19, v28, v19
	v_sub_f32_e32 v22, v21, v25
	v_mul_f32_e32 v19, v23, v19
	v_sub_f32_e32 v22, v26, v22
	v_add_f32_e32 v19, v22, v19
	v_mul_f32_e32 v25, 0x3f317218, v20
	v_add_f32_e32 v22, v21, v19
	v_fma_f32 v26, v20, s1, -v25
	v_mul_f32_e32 v23, v22, v22
	v_mov_b32_e32 v24, 0x3ecc95a3
	v_fmac_f32_e32 v26, 0xb102e308, v20
	v_sub_f32_e32 v20, v22, v21
	v_fmamk_f32 v24, v23, 0x3e9b6dac, v24
	v_sub_f32_e32 v19, v19, v20
	v_add_f32_e32 v20, v25, v26
	v_fmaak_f32 v24, v23, v24, 0x3f2aaada
	v_sub_f32_e32 v21, v20, v25
	v_ldexp_f32 v25, v22, 1
	v_mul_f32_e32 v22, v22, v23
	v_mul_f32_e32 v22, v22, v24
	v_add_f32_e32 v23, v25, v22
	v_sub_f32_e32 v24, v23, v25
	v_ldexp_f32 v19, v19, 1
	v_sub_f32_e32 v22, v22, v24
	v_add_f32_e32 v19, v19, v22
	v_add_f32_e32 v22, v23, v19
	v_sub_f32_e32 v23, v22, v23
	v_sub_f32_e32 v19, v19, v23
	v_add_f32_e32 v23, v20, v22
	v_sub_f32_e32 v24, v23, v20
	v_sub_f32_e32 v25, v23, v24
	v_sub_f32_e32 v21, v26, v21
	v_sub_f32_e32 v20, v20, v25
	v_sub_f32_e32 v22, v22, v24
	v_add_f32_e32 v20, v22, v20
	v_add_f32_e32 v22, v21, v19
	v_sub_f32_e32 v24, v22, v21
	v_sub_f32_e32 v25, v22, v24
	v_sub_f32_e32 v21, v21, v25
	v_sub_f32_e32 v19, v19, v24
	v_add_f32_e32 v20, v22, v20
	v_add_f32_e32 v19, v19, v21
	v_add_f32_e32 v21, v23, v20
	v_sub_f32_e32 v22, v21, v23
	v_sub_f32_e32 v20, v20, v22
	v_add_f32_e32 v19, v19, v20
	s_mov_b32 s1, 0x7f800000
	v_add_f32_e32 v19, v21, v19
	v_cmp_neq_f32_e32 vcc, s1, v11
	s_mov_b32 s1, 0x33800000
	s_nop 0
	v_cndmask_b32_e32 v19, v228, v19, vcc
	v_cmp_lt_f32_e64 vcc, |v11|, s1
	s_movk_i32 s1, 0x3fff
	s_nop 0
	v_cndmask_b32_e32 v11, v19, v11, vcc
	v_sub_f32_e32 v19, v0, v11
	v_cmp_lt_i32_e32 vcc, s1, v10
	s_and_saveexec_b64 s[6:7], vcc
	s_xor_b64 s[18:19], exec, s[6:7]
	s_cbranch_execz .LBB0_340
	v_mov_b32_e32 v11, v1
	v_lshl_add_u64 v[10:11], v[10:11], 2, v[6:7]
	v_add_co_u32_e32 v20, vcc, 0xffff0000, v10
	s_nop 1
	v_addc_co_u32_e32 v21, vcc, -1, v11, vcc
	global_store_dword v[20:21], v19, off
	v_add_co_u32_e32 v20, vcc, 0x10000, v10
	s_nop 1
	v_addc_co_u32_e32 v21, vcc, 0, v11, vcc
	global_store_dword v[20:21], v19, off offset:2048
	v_add_co_u32_e32 v20, vcc, 0x31000, v10
	s_nop 1
	v_addc_co_u32_e32 v21, vcc, 0, v11, vcc
	v_add_co_u32_e32 v10, vcc, 0x51000, v10
	global_store_dword v[20:21], v19, off
	s_nop 0
	v_addc_co_u32_e32 v11, vcc, 0, v11, vcc
	global_store_dword v[10:11], v19, off offset:2048
